# quant_gu side job in P4: common path without taken branches (stores, item start, wait variants out of line)
# speedup vs baseline: 1.0016x; 1.0016x over previous
.Lp4_body:
	s_add_i32 s8, s71, 2
	s_add_u32 s28, s26, 0xfff00080
	s_addc_u32 s29, s27, -1
	s_cmp_eq_u32 s68, s71
	s_cselect_b32 s31, s64, s29
	s_cselect_b32 s30, s65, s28
	s_cselect_b32 s29, s66, s70
	s_cselect_b32 s28, s67, s69
	v_add_u32_e32 v5, s53, v163
	ds_read_b128 v[172:175], v5
	ds_read_b128 v[176:179], v5 offset:1024
	ds_read_b128 v[180:183], v5 offset:2048
	ds_read_b128 v[184:187], v5 offset:3072
	v_add_u32_e32 v5, s54, v163
	ds_read_b128 v[188:191], v5
	ds_read_b128 v[192:195], v5 offset:1024
	ds_read_b128 v[196:199], v5 offset:2048
	ds_read_b128 v[200:203], v5 offset:3072
	s_add_i32 m0, s43, 0xc000
	ds_read_b128 v[204:207], v166
	ds_read_b128 v[208:211], v166 offset:1024
	ds_read_b128 v[212:215], v166 offset:2048
	ds_read_b128 v[216:219], v166 offset:3072
	ds_read_b128 v[220:223], v166 offset:4096
	ds_read_b128 v[224:227], v166 offset:5120
	ds_read_b128 v[236:239], v166 offset:6144
	ds_read_b128 v[240:243], v166 offset:7168
	global_load_lds_dwordx4 v146, s[26:27]
	s_add_i32 m0, s43, 0xe000
	s_nop 0
	global_load_lds_dwordx4 v148, s[26:27]
	s_bitcmp1_b32 s32, 31
	s_cbranch_scc1 .Lg_st_p
	s_mov_b32 s32, 0

.Lg_ld_p:
	global_load_dwordx4 v[244:247], v137, s[100:101] nt
	s_add_u32 s100, s100, 0xac00
	s_addc_u32 s101, s101, 0
	s_or_b32 s32, s32, 1
	s_and_b32 s75, s84, 3
	s_add_u32 s84, s84, 1
	s_cmp_eq_u32 s75, 3
	s_cbranch_scc1 .Lg_p_p
.Lg_w_p:
	s_bitcmp1_b32 s32, 2
	s_cbranch_scc1 .LgW1_p_st
	s_bitcmp1_b32 s32, 0
	s_cbranch_scc0 .LgW1_p_0
	s_waitcnt vmcnt(9)
.LgW1_p_x:
	s_waitcnt lgkmcnt(0)
	s_barrier
	s_setprio 1
	s_waitcnt lgkmcnt(0)
	v_mfma_f32_16x16x32_bf16 v[132:135], v[172:175], v[204:207], v[132:135]
	v_mfma_f32_16x16x32_bf16 v[128:131], v[180:183], v[204:207], v[128:131]
	v_mfma_f32_16x16x32_bf16 v[116:119], v[172:175], v[212:215], v[116:119]
	v_mfma_f32_16x16x32_bf16 v[112:115], v[180:183], v[212:215], v[112:115]
	v_mfma_f32_16x16x32_bf16 v[100:103], v[172:175], v[220:223], v[100:103]
	v_mfma_f32_16x16x32_bf16 v[96:99], v[180:183], v[220:223], v[96:99]
	v_mfma_f32_16x16x32_bf16 v[84:87], v[172:175], v[236:239], v[84:87]
	v_mfma_f32_16x16x32_bf16 v[80:83], v[180:183], v[236:239], v[80:83]
	v_mfma_f32_16x16x32_bf16 v[132:135], v[176:179], v[208:211], v[132:135]
	v_mfma_f32_16x16x32_bf16 v[128:131], v[184:187], v[208:211], v[128:131]
	v_mfma_f32_16x16x32_bf16 v[116:119], v[176:179], v[216:219], v[116:119]
	v_mfma_f32_16x16x32_bf16 v[112:115], v[184:187], v[216:219], v[112:115]
	v_mfma_f32_16x16x32_bf16 v[100:103], v[176:179], v[224:227], v[100:103]
	v_mfma_f32_16x16x32_bf16 v[96:99], v[184:187], v[224:227], v[96:99]
	v_mfma_f32_16x16x32_bf16 v[84:87], v[176:179], v[240:243], v[84:87]
	v_mfma_f32_16x16x32_bf16 v[80:83], v[184:187], v[240:243], v[80:83]
	s_setprio 0
	s_setprio 1
	v_mfma_f32_16x16x32_bf16 v[124:127], v[188:191], v[204:207], v[124:127]
	v_mfma_f32_16x16x32_bf16 v[120:123], v[196:199], v[204:207], v[120:123]
	v_mfma_f32_16x16x32_bf16 v[108:111], v[188:191], v[212:215], v[108:111]
	v_mfma_f32_16x16x32_bf16 v[104:107], v[196:199], v[212:215], v[104:107]
	v_mfma_f32_16x16x32_bf16 v[92:95], v[188:191], v[220:223], v[92:95]
	v_mfma_f32_16x16x32_bf16 v[88:91], v[196:199], v[220:223], v[88:91]
	v_mfma_f32_16x16x32_bf16 v[76:79], v[188:191], v[236:239], v[76:79]
	v_mfma_f32_16x16x32_bf16 v[72:75], v[196:199], v[236:239], v[72:75]
	v_mfma_f32_16x16x32_bf16 v[124:127], v[192:195], v[208:211], v[124:127]
	v_mfma_f32_16x16x32_bf16 v[120:123], v[200:203], v[208:211], v[120:123]
	v_mfma_f32_16x16x32_bf16 v[108:111], v[192:195], v[216:219], v[108:111]
	v_mfma_f32_16x16x32_bf16 v[104:107], v[200:203], v[216:219], v[104:107]
	v_mfma_f32_16x16x32_bf16 v[92:95], v[192:195], v[224:227], v[92:95]
	v_mfma_f32_16x16x32_bf16 v[88:91], v[200:203], v[224:227], v[88:91]
	v_mfma_f32_16x16x32_bf16 v[76:79], v[192:195], v[240:243], v[76:79]
	v_mfma_f32_16x16x32_bf16 v[72:75], v[200:203], v[240:243], v[72:75]
	s_setprio 0
	s_barrier
	s_add_i32 s71, s53, s40
	s_mov_b32 m0, s71
	ds_read_b128 v[204:207], v166 offset:16384
	ds_read_b128 v[208:211], v166 offset:17408
	ds_read_b128 v[212:215], v166 offset:18432
	ds_read_b128 v[216:219], v166 offset:19456
	ds_read_b128 v[220:223], v166 offset:20480
	ds_read_b128 v[224:227], v166 offset:21504
	ds_read_b128 v[236:239], v166 offset:22528
	ds_read_b128 v[240:243], v166 offset:23552
	global_load_lds_dwordx4 v138, s[28:29]
	s_add_i32 m0, s71, 0x2000
	s_add_u32 s72, s28, 0x100000
	s_addc_u32 s73, s29, 0
	s_add_i32 s71, s54, s40
	global_load_lds_dwordx4 v142, s[28:29]
	s_mov_b32 m0, s71
	s_nop 0
	global_load_lds_dwordx4 v138, s[72:73]
	s_add_i32 m0, s71, 0x2000
	s_nop 0
	global_load_lds_dwordx4 v142, s[72:73]
	s_mov_b32 m0, s43
	s_nop 0
	global_load_lds_dwordx4 v136, s[30:31]
	s_mov_b32 m0, s44
	s_nop 0
	global_load_lds_dwordx4 v140, s[30:31]
	s_bitcmp1_b32 s32, 2
	s_cbranch_scc1 .LgW2_p_st
	s_bitcmp1_b32 s32, 0
	s_cbranch_scc0 .LgW2_p_0
	s_waitcnt vmcnt(9)
.LgW2_p_x:
	s_waitcnt lgkmcnt(0)
	s_barrier
	s_setprio 1
	s_waitcnt lgkmcnt(0)
	v_mfma_f32_16x16x32_bf16 v[68:71], v[172:175], v[204:207], v[68:71]
	v_mfma_f32_16x16x32_bf16 v[64:67], v[180:183], v[204:207], v[64:67]
	v_mfma_f32_16x16x32_bf16 v[52:55], v[172:175], v[212:215], v[52:55]
	v_mfma_f32_16x16x32_bf16 v[48:51], v[180:183], v[212:215], v[48:51]
	v_mfma_f32_16x16x32_bf16 v[36:39], v[172:175], v[220:223], v[36:39]
	v_mfma_f32_16x16x32_bf16 v[32:35], v[180:183], v[220:223], v[32:35]
	v_mfma_f32_16x16x32_bf16 v[20:23], v[172:175], v[236:239], v[20:23]
	v_mfma_f32_16x16x32_bf16 v[16:19], v[180:183], v[236:239], v[16:19]
	v_mfma_f32_16x16x32_bf16 v[68:71], v[176:179], v[208:211], v[68:71]
	v_mfma_f32_16x16x32_bf16 v[64:67], v[184:187], v[208:211], v[64:67]
	v_mfma_f32_16x16x32_bf16 v[52:55], v[176:179], v[216:219], v[52:55]
	v_mfma_f32_16x16x32_bf16 v[48:51], v[184:187], v[216:219], v[48:51]
	v_mfma_f32_16x16x32_bf16 v[36:39], v[176:179], v[224:227], v[36:39]
	v_mfma_f32_16x16x32_bf16 v[32:35], v[184:187], v[224:227], v[32:35]
	v_mfma_f32_16x16x32_bf16 v[20:23], v[176:179], v[240:243], v[20:23]
	v_mfma_f32_16x16x32_bf16 v[16:19], v[184:187], v[240:243], v[16:19]
	s_setprio 0
	s_setprio 1
	v_mfma_f32_16x16x32_bf16 v[60:63], v[188:191], v[204:207], v[60:63]
	v_mfma_f32_16x16x32_bf16 v[56:59], v[196:199], v[204:207], v[56:59]
	v_mfma_f32_16x16x32_bf16 v[44:47], v[188:191], v[212:215], v[44:47]
	v_mfma_f32_16x16x32_bf16 v[40:43], v[196:199], v[212:215], v[40:43]
	v_mfma_f32_16x16x32_bf16 v[28:31], v[188:191], v[220:223], v[28:31]
	v_mfma_f32_16x16x32_bf16 v[24:27], v[196:199], v[220:223], v[24:27]
	v_mfma_f32_16x16x32_bf16 v[12:15], v[188:191], v[236:239], v[12:15]
	v_mfma_f32_16x16x32_bf16 v[6:9], v[196:199], v[236:239], v[8:11]
	v_mfma_f32_16x16x32_bf16 v[60:63], v[192:195], v[208:211], v[60:63]
	v_mfma_f32_16x16x32_bf16 v[56:59], v[200:203], v[208:211], v[56:59]
	v_mfma_f32_16x16x32_bf16 v[44:47], v[192:195], v[216:219], v[44:47]
	v_mfma_f32_16x16x32_bf16 v[40:43], v[200:203], v[216:219], v[40:43]
	v_mfma_f32_16x16x32_bf16 v[28:31], v[192:195], v[224:227], v[28:31]
	v_mfma_f32_16x16x32_bf16 v[24:27], v[200:203], v[224:227], v[24:27]
	v_mfma_f32_16x16x32_bf16 v[12:15], v[192:195], v[240:243], v[12:15]
	v_mfma_f32_16x16x32_bf16 v[6:9], v[200:203], v[240:243], v[6:9]
	s_setprio 0
	s_barrier
	s_add_i32 s71, 0, 0x18000
	v_add_u32_e32 v5, s71, v163
	s_add_i32 s72, 0, 0x1c000
	ds_read_b128 v[172:175], v5
	ds_read_b128 v[176:179], v5 offset:1024
	ds_read_b128 v[180:183], v5 offset:2048
	ds_read_b128 v[184:187], v5 offset:3072
	v_add_u32_e32 v5, s72, v163
	ds_read_b128 v[188:191], v5
	ds_read_b128 v[192:195], v5 offset:1024
	ds_read_b128 v[196:199], v5 offset:2048
	ds_read_b128 v[200:203], v5 offset:3072
	s_add_u32 s30, s30, 0x100000
	s_addc_u32 s31, s31, 0
	s_mov_b32 m0, s45
	ds_read_b128 v[204:207], v166 offset:32768
	ds_read_b128 v[208:211], v166 offset:33792
	ds_read_b128 v[212:215], v166 offset:34816
	ds_read_b128 v[216:219], v166 offset:35840
	ds_read_b128 v[220:223], v166 offset:36864
	ds_read_b128 v[224:227], v166 offset:37888
	ds_read_b128 v[236:239], v166 offset:38912
	ds_read_b128 v[240:243], v166 offset:39936
	global_load_lds_dwordx4 v136, s[30:31]
	s_mov_b32 m0, s46
	s_nop 0
	global_load_lds_dwordx4 v140, s[30:31]
	s_bitcmp1_b32 s32, 2
	s_cbranch_scc1 .LgW3_p_st
	s_bitcmp1_b32 s32, 0
	s_cbranch_scc0 .LgW3_p_0
	s_waitcnt vmcnt(9)

.Lg_st_p:
	s_sub_u32 s75, s84, 4
	s_bfe_u32 s75, s75, 0x20002
	s_lshl_b32 s75, s75, 2
	s_add_u32 s76, s98, s75
	s_addc_u32 s77, s99, 0
	v_mbcnt_lo_u32_b32 v244, -1, 0
	v_mbcnt_hi_u32_b32 v244, -1, v244
	v_and_b32_e32 v245, 7, v244
	v_lshrrev_b32_e32 v244, 3, v244
	v_lshlrev_b32_e32 v244, 4, v244
	v_lshl_add_u32 v244, v245, 14, v244
	global_store_dword v244, v248, s[76:77]
	s_add_u32 s76, s76, 0x1000
	s_addc_u32 s77, s77, 0
	global_store_dword v244, v249, s[76:77]
	s_add_u32 s76, s76, 0x1000
	s_addc_u32 s77, s77, 0
	global_store_dword v244, v255, s[76:77]
	s_add_u32 s76, s76, 0x1000
	s_addc_u32 s77, s77, 0
	global_store_dword v244, v149, s[76:77]
	s_mov_b32 s32, 4
	s_branch .Lg_a_p
.Lg_p_p:
	s_bitset1_b32 s32, 31
	s_branch .Lg_w_p
.LgW1_p_0:
	s_waitcnt vmcnt(8)
	s_branch .LgW1_p_x
.LgW1_p_st:
	s_bitcmp1_b32 s32, 0
	s_cbranch_scc0 .LgW1_p_s0
	s_waitcnt vmcnt(13)
	s_branch .LgW1_p_x
.LgW1_p_s0:
	s_waitcnt vmcnt(12)
	s_branch .LgW1_p_x

.LgW1_s_0:
	s_waitcnt vmcnt(10)
	s_branch .LgW1_s_x
.LgW1_s_st:
	s_bitcmp1_b32 s32, 0
	s_cbranch_scc0 .LgW1_s_s0
	s_waitcnt vmcnt(15)
	s_branch .LgW1_s_x
.LgW1_s_s0:
	s_waitcnt vmcnt(14)
	s_branch .LgW1_s_x

.LBB0_1033:
	s_add_i32 s8, s71, 2
	s_add_u32 s28, s26, 0xfff00080
	s_addc_u32 s29, s27, -1
	s_cmp_eq_u32 s68, s71
	s_cselect_b32 s31, s64, s29
	s_cselect_b32 s30, s65, s28
	s_cselect_b32 s29, s66, s70
	s_cselect_b32 s28, s67, s69
	s_cmpk_lt_i32 s3, 0x56
	s_cselect_b32 s71, s52, 0x2b00
	s_mov_b32 s72, 0xac00
	s_cselect_b32 s74, s72, 0x4000
	s_sub_i32 s71, s71, s33
	v_min3_i32 v5, s71, v160, 2
	v_sub_u32_e32 v160, v160, v5
	v_readfirstlane_b32 s71, v5
	s_max_i32 s72, s71, 0
	s_add_i32 s72, s33, s72
	s_add_i32 s75, s72, -1
	s_min_i32 s72, s33, s75
	s_mul_hi_i32 s73, s74, s72
	s_mul_i32 s72, s74, s72
	s_add_u32 s72, s34, s72
	s_addc_u32 s73, s35, s73
	s_mul_hi_i32 s76, s74, s75
	s_mul_i32 s74, s74, s75
	s_add_u32 s74, s34, s74
	global_load_dwordx4 v[152:155], v159, s[72:73] nt
	s_addc_u32 s75, s35, s76
	global_load_dwordx4 v[168:171], v159, s[74:75] nt
	s_add_i32 s33, s71, s33
	v_add_u32_e32 v5, s53, v163
	ds_read_b128 v[172:175], v5
	ds_read_b128 v[176:179], v5 offset:1024
	ds_read_b128 v[180:183], v5 offset:2048
	ds_read_b128 v[184:187], v5 offset:3072
	v_add_u32_e32 v5, s54, v163
	ds_read_b128 v[188:191], v5
	ds_read_b128 v[192:195], v5 offset:1024
	ds_read_b128 v[196:199], v5 offset:2048
	ds_read_b128 v[200:203], v5 offset:3072
	s_add_i32 m0, s43, 0xc000
	ds_read_b128 v[204:207], v166
	ds_read_b128 v[208:211], v166 offset:1024
	ds_read_b128 v[212:215], v166 offset:2048
	ds_read_b128 v[216:219], v166 offset:3072
	ds_read_b128 v[220:223], v166 offset:4096
	ds_read_b128 v[224:227], v166 offset:5120
	ds_read_b128 v[236:239], v166 offset:6144
	ds_read_b128 v[240:243], v166 offset:7168
	global_load_lds_dwordx4 v146, s[26:27]
	s_add_i32 m0, s43, 0xe000
	s_nop 0
	global_load_lds_dwordx4 v148, s[26:27]
	s_bitcmp1_b32 s32, 31
	s_cbranch_scc1 .Lg_st_s
	s_mov_b32 s32, 0

.Lg_w_s:
	s_bitcmp1_b32 s32, 2
	s_cbranch_scc1 .LgW1_s_st
	s_bitcmp1_b32 s32, 0
	s_cbranch_scc0 .LgW1_s_0
	s_waitcnt vmcnt(11)
.LgW1_s_x:
	s_waitcnt lgkmcnt(0)
	s_barrier
	s_setprio 1
	s_waitcnt lgkmcnt(0)
	v_mfma_f32_16x16x32_bf16 v[132:135], v[172:175], v[204:207], v[132:135]
	v_mfma_f32_16x16x32_bf16 v[128:131], v[180:183], v[204:207], v[128:131]
	v_mfma_f32_16x16x32_bf16 v[116:119], v[172:175], v[212:215], v[116:119]
	v_mfma_f32_16x16x32_bf16 v[112:115], v[180:183], v[212:215], v[112:115]
	v_mfma_f32_16x16x32_bf16 v[100:103], v[172:175], v[220:223], v[100:103]
	v_mfma_f32_16x16x32_bf16 v[96:99], v[180:183], v[220:223], v[96:99]
	v_mfma_f32_16x16x32_bf16 v[84:87], v[172:175], v[236:239], v[84:87]
	v_mfma_f32_16x16x32_bf16 v[80:83], v[180:183], v[236:239], v[80:83]
	v_mfma_f32_16x16x32_bf16 v[132:135], v[176:179], v[208:211], v[132:135]
	v_mfma_f32_16x16x32_bf16 v[128:131], v[184:187], v[208:211], v[128:131]
	v_mfma_f32_16x16x32_bf16 v[116:119], v[176:179], v[216:219], v[116:119]
	v_mfma_f32_16x16x32_bf16 v[112:115], v[184:187], v[216:219], v[112:115]
	v_mfma_f32_16x16x32_bf16 v[100:103], v[176:179], v[224:227], v[100:103]
	v_mfma_f32_16x16x32_bf16 v[96:99], v[184:187], v[224:227], v[96:99]
	v_mfma_f32_16x16x32_bf16 v[84:87], v[176:179], v[240:243], v[84:87]
	v_mfma_f32_16x16x32_bf16 v[80:83], v[184:187], v[240:243], v[80:83]
	s_setprio 0
	s_setprio 1
	v_mfma_f32_16x16x32_bf16 v[124:127], v[188:191], v[204:207], v[124:127]
	v_mfma_f32_16x16x32_bf16 v[120:123], v[196:199], v[204:207], v[120:123]
	v_mfma_f32_16x16x32_bf16 v[108:111], v[188:191], v[212:215], v[108:111]
	v_mfma_f32_16x16x32_bf16 v[104:107], v[196:199], v[212:215], v[104:107]
	v_mfma_f32_16x16x32_bf16 v[92:95], v[188:191], v[220:223], v[92:95]
	v_mfma_f32_16x16x32_bf16 v[88:91], v[196:199], v[220:223], v[88:91]
	v_mfma_f32_16x16x32_bf16 v[76:79], v[188:191], v[236:239], v[76:79]
	v_mfma_f32_16x16x32_bf16 v[72:75], v[196:199], v[236:239], v[72:75]
	v_mfma_f32_16x16x32_bf16 v[124:127], v[192:195], v[208:211], v[124:127]
	v_mfma_f32_16x16x32_bf16 v[120:123], v[200:203], v[208:211], v[120:123]
	v_mfma_f32_16x16x32_bf16 v[108:111], v[192:195], v[216:219], v[108:111]
	v_mfma_f32_16x16x32_bf16 v[104:107], v[200:203], v[216:219], v[104:107]
	v_mfma_f32_16x16x32_bf16 v[92:95], v[192:195], v[224:227], v[92:95]
	v_mfma_f32_16x16x32_bf16 v[88:91], v[200:203], v[224:227], v[88:91]
	v_mfma_f32_16x16x32_bf16 v[76:79], v[192:195], v[240:243], v[76:79]
	v_mfma_f32_16x16x32_bf16 v[72:75], v[200:203], v[240:243], v[72:75]
	s_setprio 0
	s_barrier
	s_add_i32 s71, s53, s40
	s_mov_b32 m0, s71
	ds_read_b128 v[204:207], v166 offset:16384
	ds_read_b128 v[208:211], v166 offset:17408
	ds_read_b128 v[212:215], v166 offset:18432
	ds_read_b128 v[216:219], v166 offset:19456
	ds_read_b128 v[220:223], v166 offset:20480
	ds_read_b128 v[224:227], v166 offset:21504
	ds_read_b128 v[236:239], v166 offset:22528
	ds_read_b128 v[240:243], v166 offset:23552
	global_load_lds_dwordx4 v138, s[28:29]
	s_add_i32 m0, s71, 0x2000
	s_add_u32 s72, s28, 0x100000
	s_addc_u32 s73, s29, 0
	s_add_i32 s71, s54, s40
	global_load_lds_dwordx4 v142, s[28:29]
	s_mov_b32 m0, s71
	s_nop 0
	global_load_lds_dwordx4 v138, s[72:73]
	s_add_i32 m0, s71, 0x2000
	s_nop 0
	global_load_lds_dwordx4 v142, s[72:73]
	s_mov_b32 m0, s43
	s_nop 0
	global_load_lds_dwordx4 v136, s[30:31]
	s_mov_b32 m0, s44
	s_nop 0
	global_load_lds_dwordx4 v140, s[30:31]
	s_bitcmp1_b32 s32, 2
	s_cbranch_scc1 .LgW2_s_st
	s_bitcmp1_b32 s32, 0
	s_cbranch_scc0 .LgW2_s_0
	s_waitcnt vmcnt(11)
